# GDN recurrence on f32 matrix cores (chunked, precomputed per-chunk inverse), FoX on all non-GDN blocks, fast layer-1 weight conversion in phase 6
# speedup vs baseline: 1.2562x; 1.0332x over previous
; __device__ __forceinline__ void prep_weights(const Params& p, int layer, int which, float* tile, int bid, int nb) {
;     ...
;   for (int s = 0; s < 2; s++) {
;     if (!((which >> s) & 1)) continue;
;     const float* win = p.ffn_w_in + (size_t)(layer * 2 + s) * 1024 * 5632;
;     const float* wout = p.ffn_w_out + (size_t)(layer * 2 + s) * 2816 * 1024;
;     bf16_t* din = wb + (s ? W0_FIN_B : W0_FIN_A);
;     bf16_t* dout = wb + (s ? W0_FOUT_B : W0_FOUT_A);
;     wjob_run(win, din, 5632, 0, 5632, 5632, 0, 1024, 0, 1024, 1024, 1, 0, nullptr, tile, bid, nb);
;     wjob_run(wout, dout, 1024, 0, 1024, 1024, 0, 2816, 0, 2816, 2816, 0, 0, nullptr, tile, bid, nb);
;   }
;   if (!(which & 4)) return;
;   if (layer == 0) {
;     bf16_t* d = wb + W0_HIN;
;     const float* s = p.hyb_w_in;
;     wjob_run(s, d, 3600, 0, 1536, 1536, 0, 1024, 0, 1024, 1024, 0, 0, nullptr, tile, bid, nb);
;     wjob_run(s, d, 3600, 1544, 1536, 1536, 1536, 1024, 0, 1024, 1024, 0, 0, nullptr, tile, bid, nb);
;     wjob_run(s, d, 3600, 3088, 512, 512, 3072, 1024, 0, 1024, 1024, 0, 0, nullptr, tile, bid, nb);
;     wjob_run(s, d, 3600, 1536, 8, 8, 3584, 1024, 0, 1024, 1024, 0, 0, nullptr, tile, bid, nb);
;     wjob_run(s, d, 3600, 3080, 8, 120, 3592, 1024, 0, 1024, 1024, 0, 0, nullptr, tile, bid, nb);
;     wjob_run(p.hyb_w_out, wb + W0_HOUT, 1024, 0, 1024, 1024, 0, 1024, 0, 1024, 1024, 0, 0, nullptr, tile, bid, nb);
;   } else {
;     bf16_t* wm = (bf16_t*)((char*)p.out + OUT_W1M) - W1_G1;
;     bf16_t* d = wm + W1_G1;
;     const float* mu = p.rwkv_mu;
;     for (int half = 0; half < 2; half++) {
;       const int sm = half ? 1 : 2;
;       const int k0 = half * 1024;
;       wjob_run(p.w_r, d, 1024, 0, 1024, 1024, 0, 2048, k0, 1024, 1024, 0, sm, mu + 0 * 1024, tile, bid, nb);
;       wjob_run(p.w_k, d, 1024, 0, 1024, 1024, 1024, 2048, k0, 1024, 1024, 0, sm, mu + 2 * 1024, tile, bid, nb);
;       wjob_run(p.w_v, d, 1024, 0, 1024, 1024, 2048, 2048, k0, 1024, 1024, 0, sm, mu + 3 * 1024, tile, bid, nb);
; __device__ __forceinline__ void run_phase(const Params& p, int ph, char* smraw, int bid, int nb) {
;     ...
;     const int rk = ((const int*)(p.ws + OFF_RANK))[bid];
;     const int np = (int)*(const unsigned*)(p.ws + OFF_NPRIM);
;     if (rk < 0) {
;       const int idle_rank = ((const int*)(p.ws + OFF_RANK))[512 + bid];
;       prep_weights(p, 1, 1 | 4, smf, idle_rank, nb - np);
;       return;
.LBB0_101:
	v_writelane_b32 v244, s14, 26
	s_mov_b64 s[12:13], -1
	s_mov_b64 s[26:27], 0
	s_andn2_b64 vcc, exec, s[4:5]
	s_mov_b32 s0, s56
	v_readlane_b32 s39, v247, 0
	v_writelane_b32 v244, s0, 27
	s_cbranch_vccnz .LBB0_415
	v_readlane_b32 s0, v247, 47
	v_readlane_b32 s1, v247, 48
	s_nop 4
	global_load_dword v8, v9, s[0:1]
	v_readlane_b32 s0, v247, 49
	v_readlane_b32 s1, v247, 50
	s_waitcnt vmcnt(0)
	v_cmp_lt_i32_e64 s[12:13], -1, v8
	s_nop 2
	global_load_dword v10, v9, s[0:1]
	v_readfirstlane_b32 s2, v8
	s_mov_b64 s[0:1], -1
	s_and_b64 vcc, exec, s[12:13]
	s_waitcnt vmcnt(0)
	v_readfirstlane_b32 s48, v10
	s_cbranch_vccnz .LBB0_413
	v_readlane_b32 s0, v247, 47
	v_readlane_b32 s1, v247, 48
	s_nop 4
	global_load_dword v8, v9, s[0:1] offset:2048
	v_readlane_b32 s0, v247, 0
	s_sub_i32 s39, s0, s48
	s_movk_i32 s0, 0x15ff
	s_waitcnt vmcnt(0)
	v_cmp_lt_i32_e32 vcc, s0, v8
	v_readfirstlane_b32 s49, v8
	v_lshrrev_b32_e32 v32, 6, v2
	v_and_b32_e32 v33, 63, v2
	v_readlane_b32 s6, v247, 3
	v_readlane_b32 s7, v247, 4
	v_readlane_b32 s20, v247, 1
	v_readlane_b32 s21, v247, 2
	v_readfirstlane_b32 s4, v32
	s_lshl_b32 s2, s49, 2
	s_add_i32 s2, s2, s4
	s_lshl_b32 s5, s39, 2
	s_add_u32 s6, s6, 0x8200000
	s_addc_u32 s7, s7, 0
.Lwq_tile:
	s_cmp_ge_u32 s2, 0xf40
	s_cbranch_scc1 .Lwq_done
	s_cmp_ge_u32 s2, 0xe40
	s_cbranch_scc0 .Lwq_j7
	v_readlane_b32 s10, v247, 19
	v_readlane_b32 s11, v247, 20
	s_sub_u32 s8, s2, 0xe40
	s_movk_i32 s12, 0x1000
	s_mov_b32 s14, 0
	s_add_u32 s16, s20, 0x6fa0000
	s_addc_u32 s17, s21, 0
	s_movk_i32 s18, 0x800
	s_movk_i32 s19, 0x0
	s_movk_i32 s13, 0x0
	s_mov_b32 s15, 0
	s_mov_b32 s9, 16
	s_branch .Lwq_go
.Lwq_j7:
	s_cmp_ge_u32 s2, 0xd40
	s_cbranch_scc0 .Lwq_j6
	s_mov_b32 s10, s76
	s_mov_b32 s11, s77
	s_sub_u32 s8, s2, 0xd40
	s_movk_i32 s12, 0x1000
	s_mov_b32 s14, 0
	s_add_u32 s16, s20, 0x6180000
	s_addc_u32 s17, s21, 0
	s_movk_i32 s18, 0x1000
	s_movk_i32 s19, 0x800
	s_movk_i32 s13, 0x800
	s_mov_b32 s15, 19
	s_mov_b32 s9, 16
	s_branch .Lwq_go
.Lwq_j6:
	s_cmp_ge_u32 s2, 0xc40
	s_cbranch_scc0 .Lwq_j5
	s_mov_b32 s10, s74
	s_mov_b32 s11, s75
	s_sub_u32 s8, s2, 0xc40
	s_movk_i32 s12, 0x1000
	s_mov_b32 s14, 0
	s_add_u32 s16, s20, 0x6180000
	s_addc_u32 s17, s21, 0
	s_movk_i32 s18, 0x1000
	s_movk_i32 s19, 0x400
	s_movk_i32 s13, 0x800
	s_mov_b32 s15, 18
	s_mov_b32 s9, 16
	s_branch .Lwq_go
.Lwq_j5:
	s_cmp_ge_u32 s2, 0xb40
	s_cbranch_scc0 .Lwq_j4
	s_mov_b32 s10, s72
	s_mov_b32 s11, s73
	s_sub_u32 s8, s2, 0xb40
	s_movk_i32 s12, 0x1000
	s_mov_b32 s14, 0
	s_add_u32 s16, s20, 0x6180000
	s_addc_u32 s17, s21, 0
	s_movk_i32 s18, 0x1000
	s_movk_i32 s19, 0x0
	s_movk_i32 s13, 0x800
	s_mov_b32 s15, 16
	s_mov_b32 s9, 16
	s_branch .Lwq_go
.Lwq_j4:
	s_cmp_ge_u32 s2, 0xa40
	s_cbranch_scc0 .Lwq_j3
	s_mov_b32 s10, s76
	s_mov_b32 s11, s77
	s_sub_u32 s8, s2, 0xa40
	s_movk_i32 s12, 0x1000
	s_mov_b32 s14, 0
	s_add_u32 s16, s20, 0x6180000
	s_addc_u32 s17, s21, 0
	s_movk_i32 s18, 0x1000
	s_movk_i32 s19, 0x800
	s_movk_i32 s13, 0x0
	s_mov_b32 s15, 35
	s_mov_b32 s9, 16
	s_branch .Lwq_go
.Lwq_j3:
	s_cmp_ge_u32 s2, 0x940
	s_cbranch_scc0 .Lwq_j2
	s_mov_b32 s10, s74
	s_mov_b32 s11, s75
	s_sub_u32 s8, s2, 0x940
	s_movk_i32 s12, 0x1000
	s_mov_b32 s14, 0
	s_add_u32 s16, s20, 0x6180000
	s_addc_u32 s17, s21, 0
	s_movk_i32 s18, 0x1000
	s_movk_i32 s19, 0x400
	s_movk_i32 s13, 0x0
	s_mov_b32 s15, 34
	s_mov_b32 s9, 16
	s_branch .Lwq_go
.Lwq_j2:
	s_cmp_ge_u32 s2, 0x840
	s_cbranch_scc0 .Lwq_j1
	s_mov_b32 s10, s72
	s_mov_b32 s11, s73
	s_sub_u32 s8, s2, 0x840
	s_movk_i32 s12, 0x1000
	s_mov_b32 s14, 0
	s_add_u32 s16, s20, 0x6180000
	s_addc_u32 s17, s21, 0
	s_movk_i32 s18, 0x1000
	s_movk_i32 s19, 0x0
	s_movk_i32 s13, 0x0
	s_mov_b32 s15, 32
	s_mov_b32 s9, 16
	s_branch .Lwq_go
.Lwq_j1:
	s_cmp_ge_u32 s2, 0x580
	s_cbranch_scc0 .Lwq_j0
	v_readlane_b32 s10, v246, 39
	v_readlane_b32 s11, v246, 40
	s_add_u32 s10, s10, 0x1600000
	s_addc_u32 s11, s11, 0
	s_sub_u32 s8, s2, 0x580
	s_movk_i32 s12, 0x1000
	s_mov_b32 s14, 0
	s_add_u32 s16, s6, 0xb00000
	s_addc_u32 s17, s7, 0
	s_movk_i32 s18, 0x1600
	s_movk_i32 s19, 0x0
	s_movk_i32 s13, 0x0
	s_mov_b32 s15, 0
	s_mov_b32 s9, 44
	s_branch .Lwq_go
.Lwq_j0:
	v_readlane_b32 s10, v246, 37
	v_readlane_b32 s11, v246, 38
	s_add_u32 s10, s10, 0x2c00000
	s_addc_u32 s11, s11, 0
	s_mov_b32 s8, s2
	s_movk_i32 s12, 0x5800
	s_mov_b32 s14, 1
	s_add_u32 s16, s6, 0x0
	s_addc_u32 s17, s7, 0
	s_movk_i32 s18, 0x800
	s_movk_i32 s19, 0x0
	s_movk_i32 s13, 0x0
	s_mov_b32 s15, 0
	s_mov_b32 s9, 16
	s_branch .Lwq_go
.Lwq_go:
	s_cmp_eq_u32 s9, 16
	s_cbranch_scc1 .Lwq_tk16
	s_mul_i32 s22, s8, 0x2e9
	s_lshr_b32 s22, s22, 15
	s_branch .Lwq_tkj
.Lwq_tk16:
	s_lshr_b32 s22, s8, 4
.Lwq_tkj:
	s_mul_i32 s23, s22, s9
	s_sub_u32 s9, s8, s23
	s_lshl_b32 s22, s22, 6
	s_lshl_b32 s9, s9, 6
	v_add_u32_e32 v36, s22, v33
	s_cmp_eq_u32 s14, 0
	s_cbranch_scc1 .Lwq_lin
	v_lshrrev_b32_e32 v37, 5, v36
	v_lshlrev_b32_e32 v37, 4, v37
	v_and_b32_e32 v34, 15, v36
	v_add_u32_e32 v34, v34, v37
	v_bfe_u32 v37, v36, 4, 1
	v_mul_u32_u24_e32 v37, 0xb00, v37
	v_add_u32_e32 v34, v34, v37
	s_branch .Lwq_col
.Lwq_lin:
	v_mov_b32_e32 v34, v36
; __device__ __forceinline__ void wjob_run(const float* jsrc, bf16_t* jdst, int jsrcld, int jsrccol0, int jncols, int jnrows, int jr0, ...
;     ...
;   for (int t = bid; t < tn * tk; t += nb) {
;     const int n0 = (t / tk) * 32, k0 = (t % tk) * 32;
;     {
;       const int tx = tid & 31, ty = tid >> 5;
;       const int n = n0 + tx;
;       int sc = -1;
;       if (n < j.ncols) {
;         if (j.perm) { int q = n >> 5, i = n & 31; sc = (i < 16) ? (q * 16 + i) : (DFF + q * 16 + i - 16); }
;         else sc = j.srccol0 + n;
;       }
; #pragma unroll
;       for (int i = 0; i < 4; i++) {
;         const int k = k0 + ty + 8 * i;
;         float v = 0.f;
;         if (sc >= 0 && k < j.ksrc) {
;           v = j.src[(size_t)k * j.srcld + sc];
.Lwq_col:
	v_lshlrev_b32_e32 v34, 2, v34
	s_mul_i32 s22, s9, s12
	s_mul_hi_u32 s23, s9, s12
	s_add_u32 s22, s10, s22
	s_addc_u32 s23, s11, s23
	v_add_u32_e32 v36, s19, v36
	v_mul_lo_u32 v35, v36, s18
	s_lshl_b32 s8, s9, 1
	s_add_i32 s8, s8, s13
	v_add_u32_e32 v35, s8, v35
	global_load_dword v40, v34, s[22:23]
	s_add_u32 s22, s22, s12
	s_addc_u32 s23, s23, 0
	global_load_dword v41, v34, s[22:23]
	s_add_u32 s22, s22, s12
	s_addc_u32 s23, s23, 0
	global_load_dword v42, v34, s[22:23]
	s_add_u32 s22, s22, s12
	s_addc_u32 s23, s23, 0
	global_load_dword v43, v34, s[22:23]
	s_add_u32 s22, s22, s12
	s_addc_u32 s23, s23, 0
	global_load_dword v44, v34, s[22:23]
	s_add_u32 s22, s22, s12
	s_addc_u32 s23, s23, 0
	global_load_dword v45, v34, s[22:23]
	s_add_u32 s22, s22, s12
	s_addc_u32 s23, s23, 0
	global_load_dword v46, v34, s[22:23]
	s_add_u32 s22, s22, s12
	s_addc_u32 s23, s23, 0
	global_load_dword v47, v34, s[22:23]
	s_add_u32 s22, s22, s12
	s_addc_u32 s23, s23, 0
	global_load_dword v48, v34, s[22:23]
	s_add_u32 s22, s22, s12
	s_addc_u32 s23, s23, 0
	global_load_dword v49, v34, s[22:23]
	s_add_u32 s22, s22, s12
	s_addc_u32 s23, s23, 0
	global_load_dword v50, v34, s[22:23]
	s_add_u32 s22, s22, s12
	s_addc_u32 s23, s23, 0
	global_load_dword v51, v34, s[22:23]
	s_add_u32 s22, s22, s12
	s_addc_u32 s23, s23, 0
	global_load_dword v52, v34, s[22:23]
	s_add_u32 s22, s22, s12
	s_addc_u32 s23, s23, 0
	global_load_dword v53, v34, s[22:23]
	s_add_u32 s22, s22, s12
	s_addc_u32 s23, s23, 0
	global_load_dword v54, v34, s[22:23]
	s_add_u32 s22, s22, s12
	s_addc_u32 s23, s23, 0
	global_load_dword v55, v34, s[22:23]
	s_add_u32 s22, s22, s12
	s_addc_u32 s23, s23, 0
	global_load_dword v56, v34, s[22:23]
	s_add_u32 s22, s22, s12
	s_addc_u32 s23, s23, 0
	global_load_dword v57, v34, s[22:23]
	s_add_u32 s22, s22, s12
	s_addc_u32 s23, s23, 0
	global_load_dword v58, v34, s[22:23]
	s_add_u32 s22, s22, s12
	s_addc_u32 s23, s23, 0
	global_load_dword v59, v34, s[22:23]
	s_add_u32 s22, s22, s12
	s_addc_u32 s23, s23, 0
	global_load_dword v60, v34, s[22:23]
	s_add_u32 s22, s22, s12
	s_addc_u32 s23, s23, 0
	global_load_dword v61, v34, s[22:23]
	s_add_u32 s22, s22, s12
	s_addc_u32 s23, s23, 0
	global_load_dword v62, v34, s[22:23]
	s_add_u32 s22, s22, s12
	s_addc_u32 s23, s23, 0
	global_load_dword v63, v34, s[22:23]
	s_add_u32 s22, s22, s12
	s_addc_u32 s23, s23, 0
	global_load_dword v64, v34, s[22:23]
	s_add_u32 s22, s22, s12
	s_addc_u32 s23, s23, 0
	global_load_dword v65, v34, s[22:23]
	s_add_u32 s22, s22, s12
	s_addc_u32 s23, s23, 0
	global_load_dword v66, v34, s[22:23]
	s_add_u32 s22, s22, s12
	s_addc_u32 s23, s23, 0
	global_load_dword v67, v34, s[22:23]
	s_add_u32 s22, s22, s12
	s_addc_u32 s23, s23, 0
	global_load_dword v68, v34, s[22:23]
	s_add_u32 s22, s22, s12
	s_addc_u32 s23, s23, 0
	global_load_dword v69, v34, s[22:23]
	s_add_u32 s22, s22, s12
	s_addc_u32 s23, s23, 0
	global_load_dword v70, v34, s[22:23]
	s_add_u32 s22, s22, s12
	s_addc_u32 s23, s23, 0
	global_load_dword v71, v34, s[22:23]
	s_add_u32 s22, s22, s12
	s_addc_u32 s23, s23, 0
	global_load_dword v72, v34, s[22:23]
	s_add_u32 s22, s22, s12
	s_addc_u32 s23, s23, 0
	global_load_dword v73, v34, s[22:23]
	s_add_u32 s22, s22, s12
	s_addc_u32 s23, s23, 0
	global_load_dword v74, v34, s[22:23]
	s_add_u32 s22, s22, s12
	s_addc_u32 s23, s23, 0
	global_load_dword v75, v34, s[22:23]
	s_add_u32 s22, s22, s12
	s_addc_u32 s23, s23, 0
	global_load_dword v76, v34, s[22:23]
	s_add_u32 s22, s22, s12
	s_addc_u32 s23, s23, 0
	global_load_dword v77, v34, s[22:23]
	s_add_u32 s22, s22, s12
	s_addc_u32 s23, s23, 0
	global_load_dword v78, v34, s[22:23]
	s_add_u32 s22, s22, s12
	s_addc_u32 s23, s23, 0
	global_load_dword v79, v34, s[22:23]
	s_add_u32 s22, s22, s12
	s_addc_u32 s23, s23, 0
	global_load_dword v80, v34, s[22:23]
	s_add_u32 s22, s22, s12
	s_addc_u32 s23, s23, 0
	global_load_dword v81, v34, s[22:23]
	s_add_u32 s22, s22, s12
	s_addc_u32 s23, s23, 0
	global_load_dword v82, v34, s[22:23]
	s_add_u32 s22, s22, s12
	s_addc_u32 s23, s23, 0
	global_load_dword v83, v34, s[22:23]
	s_add_u32 s22, s22, s12
	s_addc_u32 s23, s23, 0
	global_load_dword v84, v34, s[22:23]
	s_add_u32 s22, s22, s12
	s_addc_u32 s23, s23, 0
	global_load_dword v85, v34, s[22:23]
	s_add_u32 s22, s22, s12
	s_addc_u32 s23, s23, 0
	global_load_dword v86, v34, s[22:23]
	s_add_u32 s22, s22, s12
	s_addc_u32 s23, s23, 0
	global_load_dword v87, v34, s[22:23]
	s_add_u32 s22, s22, s12
	s_addc_u32 s23, s23, 0
	global_load_dword v88, v34, s[22:23]
	s_add_u32 s22, s22, s12
	s_addc_u32 s23, s23, 0
	global_load_dword v89, v34, s[22:23]
	s_add_u32 s22, s22, s12
	s_addc_u32 s23, s23, 0
	global_load_dword v90, v34, s[22:23]
	s_add_u32 s22, s22, s12
	s_addc_u32 s23, s23, 0
	global_load_dword v91, v34, s[22:23]
	s_add_u32 s22, s22, s12
	s_addc_u32 s23, s23, 0
	global_load_dword v92, v34, s[22:23]
	s_add_u32 s22, s22, s12
	s_addc_u32 s23, s23, 0
	global_load_dword v93, v34, s[22:23]
	s_add_u32 s22, s22, s12
	s_addc_u32 s23, s23, 0
	global_load_dword v94, v34, s[22:23]
	s_add_u32 s22, s22, s12
	s_addc_u32 s23, s23, 0
	global_load_dword v95, v34, s[22:23]
	s_add_u32 s22, s22, s12
	s_addc_u32 s23, s23, 0
	global_load_dword v96, v34, s[22:23]
	s_add_u32 s22, s22, s12
	s_addc_u32 s23, s23, 0
	global_load_dword v97, v34, s[22:23]
	s_add_u32 s22, s22, s12
	s_addc_u32 s23, s23, 0
	global_load_dword v98, v34, s[22:23]
	s_add_u32 s22, s22, s12
	s_addc_u32 s23, s23, 0
	global_load_dword v99, v34, s[22:23]
	s_add_u32 s22, s22, s12
	s_addc_u32 s23, s23, 0
	global_load_dword v100, v34, s[22:23]
	s_add_u32 s22, s22, s12
	s_addc_u32 s23, s23, 0
	global_load_dword v101, v34, s[22:23]
	s_add_u32 s22, s22, s12
	s_addc_u32 s23, s23, 0
	global_load_dword v102, v34, s[22:23]
	s_add_u32 s22, s22, s12
	s_addc_u32 s23, s23, 0
	global_load_dword v103, v34, s[22:23]
	s_add_u32 s22, s22, s12
	s_addc_u32 s23, s23, 0
	s_cmp_eq_u32 s15, 0
	s_cbranch_scc1 .Lwq_nosc
	s_and_b32 s8, s15, 15
	s_lshl_b32 s8, s8, 12
	s_lshl_b32 s22, s9, 2
	s_add_i32 s8, s8, s22
	v_lshl_add_u32 v37, v33, 2, s8
	global_load_dword v38, v37, s[70:71]
	s_waitcnt vmcnt(0)
	s_bitcmp1_b32 s15, 5
	s_cbranch_scc0 .Lwq_mu1
	v_sub_f32_e32 v38, 1.0, v38
; __device__ __forceinline__ void wjob_run(const float* jsrc, bf16_t* jdst, int jsrcld, int jsrccol0, int jncols, int jnrows, int jr0, ...
;     ...
;         if (sc >= 0 && k < j.ksrc) {
;           v = j.src[(size_t)k * j.srcld + sc];
;           if (j.smode == 1) v *= j.mu[k]; else if (j.smode == 2) v *= (1.f - j.mu[k]);
;         }
;         tile[(ty + 8 * i) * 33 + tx] = v;
;       }
;     }
;     __syncthreads();
;     {
;       const int kx = tid & 31, ny = tid >> 5;
; #pragma unroll
;       for (int i = 0; i < 4; i++) {
;         const int n = n0 + ny + 8 * i;
;         if (n < j.nrows) j.dst[(size_t)(j.r0 + n) * j.dstld + j.dstk0 + k0 + kx] = f2bf(tile[kx * 33 + ny + 8 * i]);
.Lwq_mu1:
	s_nop 0
	v_readlane_b32 s22, v38, 0
	v_readlane_b32 s23, v38, 1
	v_readlane_b32 s8, v38, 2
	v_mul_f32_e32 v40, s22, v40
	v_readlane_b32 s22, v38, 3
	v_mul_f32_e32 v41, s23, v41
	v_readlane_b32 s23, v38, 4
	v_mul_f32_e32 v42, s8, v42
	v_readlane_b32 s8, v38, 5
	v_mul_f32_e32 v43, s22, v43
	v_readlane_b32 s22, v38, 6
	v_mul_f32_e32 v44, s23, v44
	v_readlane_b32 s23, v38, 7
	v_mul_f32_e32 v45, s8, v45
	v_readlane_b32 s8, v38, 8
	v_mul_f32_e32 v46, s22, v46
	v_readlane_b32 s22, v38, 9
	v_mul_f32_e32 v47, s23, v47
	v_readlane_b32 s23, v38, 10
	v_mul_f32_e32 v48, s8, v48
	v_readlane_b32 s8, v38, 11
	v_mul_f32_e32 v49, s22, v49
	v_readlane_b32 s22, v38, 12
	v_mul_f32_e32 v50, s23, v50
	v_readlane_b32 s23, v38, 13
	v_mul_f32_e32 v51, s8, v51
	v_readlane_b32 s8, v38, 14
	v_mul_f32_e32 v52, s22, v52
	v_readlane_b32 s22, v38, 15
	v_mul_f32_e32 v53, s23, v53
	v_readlane_b32 s23, v38, 16
	v_mul_f32_e32 v54, s8, v54
	v_readlane_b32 s8, v38, 17
	v_mul_f32_e32 v55, s22, v55
	v_readlane_b32 s22, v38, 18
	v_mul_f32_e32 v56, s23, v56
	v_readlane_b32 s23, v38, 19
	v_mul_f32_e32 v57, s8, v57
	v_readlane_b32 s8, v38, 20
	v_mul_f32_e32 v58, s22, v58
	v_readlane_b32 s22, v38, 21
	v_mul_f32_e32 v59, s23, v59
	v_readlane_b32 s23, v38, 22
	v_mul_f32_e32 v60, s8, v60
	v_readlane_b32 s8, v38, 23
	v_mul_f32_e32 v61, s22, v61
	v_readlane_b32 s22, v38, 24
	v_mul_f32_e32 v62, s23, v62
	v_readlane_b32 s23, v38, 25
	v_mul_f32_e32 v63, s8, v63
	v_readlane_b32 s8, v38, 26
	v_mul_f32_e32 v64, s22, v64
	v_readlane_b32 s22, v38, 27
	v_mul_f32_e32 v65, s23, v65
	v_readlane_b32 s23, v38, 28
	v_mul_f32_e32 v66, s8, v66
	v_readlane_b32 s8, v38, 29
	v_mul_f32_e32 v67, s22, v67
	v_readlane_b32 s22, v38, 30
	v_mul_f32_e32 v68, s23, v68
	v_readlane_b32 s23, v38, 31
	v_mul_f32_e32 v69, s8, v69
	v_readlane_b32 s8, v38, 32
	v_mul_f32_e32 v70, s22, v70
	v_readlane_b32 s22, v38, 33
	v_mul_f32_e32 v71, s23, v71
	v_readlane_b32 s23, v38, 34
	v_mul_f32_e32 v72, s8, v72
	v_readlane_b32 s8, v38, 35
	v_mul_f32_e32 v73, s22, v73
	v_readlane_b32 s22, v38, 36
	v_mul_f32_e32 v74, s23, v74
	v_readlane_b32 s23, v38, 37
	v_mul_f32_e32 v75, s8, v75
	v_readlane_b32 s8, v38, 38
	v_mul_f32_e32 v76, s22, v76
	v_readlane_b32 s22, v38, 39
	v_mul_f32_e32 v77, s23, v77
	v_readlane_b32 s23, v38, 40
	v_mul_f32_e32 v78, s8, v78
	v_readlane_b32 s8, v38, 41
	v_mul_f32_e32 v79, s22, v79
	v_readlane_b32 s22, v38, 42
	v_mul_f32_e32 v80, s23, v80
	v_readlane_b32 s23, v38, 43
	v_mul_f32_e32 v81, s8, v81
	v_readlane_b32 s8, v38, 44
	v_mul_f32_e32 v82, s22, v82
	v_readlane_b32 s22, v38, 45
	v_mul_f32_e32 v83, s23, v83
	v_readlane_b32 s23, v38, 46
	v_mul_f32_e32 v84, s8, v84
	v_readlane_b32 s8, v38, 47
	v_mul_f32_e32 v85, s22, v85
	v_readlane_b32 s22, v38, 48
	v_mul_f32_e32 v86, s23, v86
	v_readlane_b32 s23, v38, 49
	v_mul_f32_e32 v87, s8, v87
	v_readlane_b32 s8, v38, 50
	v_mul_f32_e32 v88, s22, v88
	v_readlane_b32 s22, v38, 51
	v_mul_f32_e32 v89, s23, v89
	v_readlane_b32 s23, v38, 52
	v_mul_f32_e32 v90, s8, v90
	v_readlane_b32 s8, v38, 53
	v_mul_f32_e32 v91, s22, v91
	v_readlane_b32 s22, v38, 54
	v_mul_f32_e32 v92, s23, v92
	v_readlane_b32 s23, v38, 55
	v_mul_f32_e32 v93, s8, v93
	v_readlane_b32 s8, v38, 56
	v_mul_f32_e32 v94, s22, v94
	v_readlane_b32 s22, v38, 57
	v_mul_f32_e32 v95, s23, v95
	v_readlane_b32 s23, v38, 58
	v_mul_f32_e32 v96, s8, v96
	v_readlane_b32 s8, v38, 59
	v_mul_f32_e32 v97, s22, v97
	v_readlane_b32 s22, v38, 60
	v_mul_f32_e32 v98, s23, v98
	v_readlane_b32 s23, v38, 61
	v_mul_f32_e32 v99, s8, v99
	v_readlane_b32 s8, v38, 62
	v_mul_f32_e32 v100, s22, v100
	v_readlane_b32 s22, v38, 63
	v_mul_f32_e32 v101, s23, v101
	v_mul_f32_e32 v102, s8, v102
	v_mul_f32_e32 v103, s22, v103
.Lwq_nosc:
	s_waitcnt vmcnt(0)
	v_cvt_pk_bf16_f32 v104, v40, v41
	v_cvt_pk_bf16_f32 v105, v42, v43
	v_cvt_pk_bf16_f32 v106, v44, v45
	v_cvt_pk_bf16_f32 v107, v46, v47
	v_cvt_pk_bf16_f32 v108, v48, v49
	v_cvt_pk_bf16_f32 v109, v50, v51
	v_cvt_pk_bf16_f32 v110, v52, v53
	v_cvt_pk_bf16_f32 v111, v54, v55
	v_cvt_pk_bf16_f32 v112, v56, v57
	v_cvt_pk_bf16_f32 v113, v58, v59
	v_cvt_pk_bf16_f32 v114, v60, v61
	v_cvt_pk_bf16_f32 v115, v62, v63
	v_cvt_pk_bf16_f32 v116, v64, v65
	v_cvt_pk_bf16_f32 v117, v66, v67
	v_cvt_pk_bf16_f32 v118, v68, v69
	v_cvt_pk_bf16_f32 v119, v70, v71
	v_cvt_pk_bf16_f32 v120, v72, v73
	v_cvt_pk_bf16_f32 v121, v74, v75
	v_cvt_pk_bf16_f32 v122, v76, v77
	v_cvt_pk_bf16_f32 v123, v78, v79
	v_cvt_pk_bf16_f32 v124, v80, v81
	v_cvt_pk_bf16_f32 v125, v82, v83
	v_cvt_pk_bf16_f32 v126, v84, v85
	v_cvt_pk_bf16_f32 v127, v86, v87
	v_cvt_pk_bf16_f32 v128, v88, v89
	v_cvt_pk_bf16_f32 v129, v90, v91
	v_cvt_pk_bf16_f32 v130, v92, v93
	v_cvt_pk_bf16_f32 v131, v94, v95
	v_cvt_pk_bf16_f32 v132, v96, v97
	v_cvt_pk_bf16_f32 v133, v98, v99
	v_cvt_pk_bf16_f32 v134, v100, v101
	v_cvt_pk_bf16_f32 v135, v102, v103
	global_store_dwordx4 v35, v[104:107], s[16:17]
	global_store_dwordx4 v35, v[108:111], s[16:17] offset:16
	global_store_dwordx4 v35, v[112:115], s[16:17] offset:32
	global_store_dwordx4 v35, v[116:119], s[16:17] offset:48
	global_store_dwordx4 v35, v[120:123], s[16:17] offset:64
	global_store_dwordx4 v35, v[124:127], s[16:17] offset:80
	global_store_dwordx4 v35, v[128:131], s[16:17] offset:96
	global_store_dwordx4 v35, v[132:135], s[16:17] offset:112
	s_add_i32 s2, s2, s5
	s_branch .Lwq_tile
.Lwq_done:
	s_mov_b64 s[12:13], 0
	v_mov_b32_e32 v8, v2
	s_branch .LBB0_128
	v_and_b32_e32 v16, 31, v8
	v_readlane_b32 s0, v247, 23
	s_waitcnt lgkmcnt(1)
	v_ashrrev_i32_e32 v17, 5, v8
	v_lshlrev_b32_e32 v8, 1, v16
	v_readlane_b32 s1, v247, 24
	s_waitcnt lgkmcnt(0)
	v_lshlrev_b32_e32 v12, 2, v16
	v_lshlrev_b32_e32 v13, 2, v17
	v_lshl_add_u64 v[10:11], s[0:1], 0, v[8:9]
	s_movk_i32 s0, 0x84
	v_mul_u32_u24_e32 v14, 0x84, v16
	v_mul_lo_u32 v8, v17, s0
	v_cmp_lt_u32_e64 s[6:7], 15, v16
	v_add_u32_e32 v18, 0xaf0, v16
	s_lshl_b32 s8, s49, 5
	s_lshl_b32 s9, s39, 5
	v_add_u32_e32 v19, v12, v8
	v_add_u32_e32 v20, v13, v14
	s_mov_b32 s10, s49
	s_branch .LBB0_106

; __device__ __forceinline__ void prep_weights(const Params& p, int layer, int which, float* tile, int bid, int nb) {
;     ...
;   for (int s = 0; s < 2; s++) {
;     if (!((which >> s) & 1)) continue;
;     const float* win = p.ffn_w_in + (size_t)(layer * 2 + s) * 1024 * 5632;
;     const float* wout = p.ffn_w_out + (size_t)(layer * 2 + s) * 2816 * 1024;
;     bf16_t* din = wb + (s ? W0_FIN_B : W0_FIN_A);
;     bf16_t* dout = wb + (s ? W0_FOUT_B : W0_FOUT_A);
;     wjob_run(win, din, 5632, 0, 5632, 5632, 0, 1024, 0, 1024, 1024, 1, 0, nullptr, tile, bid, nb);
;     wjob_run(wout, dout, 1024, 0, 1024, 1024, 0, 2816, 0, 2816, 2816, 0, 0, nullptr, tile, bid, nb);
;   }
.LBB0_128:
	s_cmpk_gt_i32 s49, 0xaff
	v_mov_b32_e32 v8, v2
	s_branch .LBB0_147
	v_and_b32_e32 v16, 31, v8
	v_readlane_b32 s0, v247, 39
	s_waitcnt lgkmcnt(1)
	v_ashrrev_i32_e32 v17, 5, v8
	v_lshlrev_b32_e32 v8, 1, v16
	v_readlane_b32 s1, v247, 40
	s_waitcnt lgkmcnt(0)
	v_lshlrev_b32_e32 v12, 2, v16
	v_lshlrev_b32_e32 v13, 2, v17
	v_lshl_add_u64 v[10:11], s[0:1], 0, v[8:9]
	s_movk_i32 s0, 0x84
	v_mul_u32_u24_e32 v14, 0x84, v16
	v_mul_lo_u32 v8, v17, s0
	s_lshl_b32 s6, s49, 5
	s_lshl_b32 s7, s39, 5
	v_add_u32_e32 v18, v12, v8
	v_add_u32_e32 v19, v13, v14
	s_mov_b32 s8, s49
	s_branch .LBB0_131

; __device__ __forceinline__ void prep_weights(const Params& p, int layer, int which, float* tile, int bid, int nb) {
;     ...
;     for (int half = 0; half < 2; half++) {
;       const int sm = half ? 1 : 2;
;       const int k0 = half * 1024;
;       wjob_run(p.w_r, d, 1024, 0, 1024, 1024, 0, 2048, k0, 1024, 1024, 0, sm, mu + 0 * 1024, tile, bid, nb);
;       wjob_run(p.w_k, d, 1024, 0, 1024, 1024, 1024, 2048, k0, 1024, 1024, 0, sm, mu + 2 * 1024, tile, bid, nb);
;       wjob_run(p.w_v, d, 1024, 0, 1024, 1024, 2048, 2048, k0, 1024, 1024, 0, sm, mu + 3 * 1024, tile, bid, nb);
;       wjob_run(p.w1, d, 64, 0, 64, 64, 3072, 2048, k0, 1024, 1024, 0, sm, mu + 1 * 1024, tile, bid, nb);
;       wjob_run(p.a1, d, 64, 0, 64, 64, 3136, 2048, k0, 1024, 1024, 0, sm, mu + 4 * 1024, tile, bid, nb);
;       wjob_run(p.g1, d, 160, 0, 160, 256, 3200, 2048, k0, 1024, 1024, 0, sm, mu + 5 * 1024, tile, bid, nb);
.LBB0_147:
	s_cmpk_lt_i32 s49, 0x400
	s_mov_b64 s[0:1], 0
	s_cmp_lt_i32 s49, 64
	s_cselect_b64 s[14:15], -1, 0
	s_cmpk_lt_i32 s49, 0x100
	s_mov_b64 s[52:53], 0
	s_mov_b64 s[4:5], -1
	s_cselect_b64 s[16:17], -1, 0
	v_cndmask_b32_e64 v16, 0, 1, s[0:1]
	s_branch .LBB0_149

; __device__ __forceinline__ void prep_weights(const Params& p, int layer, int which, float* tile, int bid, int nb) {
;     ...
;       wjob_run(p.w1, d, 64, 0, 64, 64, 3072, 2048, k0, 1024, 1024, 0, sm, mu + 1 * 1024, tile, bid, nb);
;       wjob_run(p.a1, d, 64, 0, 64, 64, 3136, 2048, k0, 1024, 1024, 0, sm, mu + 4 * 1024, tile, bid, nb);
;       wjob_run(p.g1, d, 160, 0, 160, 256, 3200, 2048, k0, 1024, 1024, 0, sm, mu + 5 * 1024, tile, bid, nb);
;     }
;     wjob_run(p.w2, wm + W1_W2, 1024, 0, 1024, 1024, 0, 64, 0, 64, 64, 0, 0, nullptr, tile, bid, nb);
;     wjob_run(p.a2, wm + W1_A2, 1024, 0, 1024, 1024, 0, 64, 0, 64, 64, 0, 0, nullptr, tile, bid, nb);
;     wjob_run(p.g2, wm + W1_G2, 1024, 0, 1024, 1024, 0, 192, 0, 160, 192, 0, 0, nullptr, tile, bid, nb);
;     wjob_run(p.w_o, wm + W1_WO, 1024, 0, 1024, 1024, 0, 1024, 0, 1024, 1024, 0, 0, nullptr, tile, bid, nb);
.LBB0_393:
	v_mov_b32_e32 v8, v2
	s_and_b64 vcc, exec, s[6:7]
	s_branch .LBB0_412
	v_and_b32_e32 v16, 31, v8
	v_readlane_b32 s0, v247, 35
	s_waitcnt lgkmcnt(1)
	v_ashrrev_i32_e32 v17, 5, v8
	v_lshlrev_b32_e32 v8, 1, v16
	v_readlane_b32 s1, v247, 36
	s_waitcnt lgkmcnt(0)
	v_lshlrev_b32_e32 v12, 2, v16
	v_lshlrev_b32_e32 v13, 2, v17
	v_lshl_add_u64 v[10:11], s[0:1], 0, v[8:9]
	s_movk_i32 s0, 0x84
	v_mul_u32_u24_e32 v14, 0x84, v16
	v_mul_lo_u32 v8, v17, s0
	s_lshl_b32 s4, s49, 5
	s_lshl_b32 s5, s39, 5
	v_add_u32_e32 v18, v12, v8
	v_add_u32_e32 v19, v13, v14
	s_branch .LBB0_396

; __device__ __forceinline__ void mixer0_phase(const Params& p, float* sm, int bid, int nb) {
;     ...
;       for (int f = bid - 128; f < nfox; f += nb - 128) {
;         const int qt = 32 - f / 32, bh = f % 32;
;         fox_item(p, bh * 33 + qt, sm);
.LBB0_412:
	v_readlane_b32 s0, v247, 49
	v_readlane_b32 s1, v247, 50
	s_nop 4
	global_load_dword v8, v9, s[0:1]
	v_readlane_b32 s0, v247, 47
	v_readlane_b32 s1, v247, 48
	s_nop 4
	global_load_dword v10, v9, s[0:1] offset:2048
	s_waitcnt vmcnt(0)
	v_readfirstlane_b32 s48, v8
	v_readfirstlane_b32 s49, v10
	s_cmpk_gt_i32 s48, 0x80
	s_cbranch_scc0 .Lidle_done
	s_add_i32 s52, s48, s49
	s_add_i32 s52, s52, 0xffffff80
	v_readlane_b32 s22, v247, 0
	s_add_i32 s22, s22, 0xffffff80
	s_mov_b64 s[26:27], 0
	s_cmpk_gt_i32 s52, 0x41f
	s_cbranch_scc1 .Lidle_done
	s_branch .LBB0_1686

; __device__ __forceinline__ void mixer0_phase(const Params& p, float* sm, int bid, int nb) {
;     ...
;       for (int f = bid - 128; f < nfox; f += nb - 128) {
;         const int qt = 32 - f / 32, bh = f % 32;
;         fox_item(p, bh * 33 + qt, sm);
.LBB0_1681:
	s_andn2_b64 vcc, exec, s[0:1]
	s_cbranch_vccnz .LBB0_1747
	v_readlane_b32 s0, v244, 27
	s_cmpk_gt_i32 s0, 0x7f
	s_mov_b64 s[0:1], -1
	s_cbranch_scc0 .LBB0_1725
	v_readlane_b32 s0, v244, 27
	s_cmpk_gt_u32 s0, 0x49f
	s_cbranch_scc1 .LBB0_1724
	v_readlane_b32 s0, v244, 27
	s_add_i32 s52, s0, 0xffffff80
	v_readlane_b32 s22, v247, 0
	s_add_i32 s22, s22, 0xffffff80
	s_branch .LBB0_1686

; __device__ __forceinline__ int otid() { int t = threadIdx.x; asm volatile("" : "+v"(t)); return t; }
; __device__ __forceinline__ void gdn_item(const Params& p, int item, float* sm) {
;   const int b = item >> 5, h = (item >> 3) & 3, c0 = (item & 7) * 16;
;   const bf16_t* gp = (const bf16_t*)p.out;
;   const float* gg = (const float*)(p.ws + OFF_GG);
;   bf16_t* O = (bf16_t*)(p.ws + OFF_O);
;   constexpr int TC = 16;
;   constexpr int BUF = 2 * TC * 128 + TC * 16 + 2 * TC + TC * 16 + TC;
;   const int tid = otid(), lane = tid & 63, wave = tid >> 6;
;   const int sub = lane & 15, cw = wave * 4 + (lane >> 4);
;   const int ltt = tid >> 4, lseg = tid & 15;
;   float S[8];
; #pragma unroll
;   for (int i = 0; i < 8; i++) S[i] = 0.f;
;   const size_t rowb = (size_t)b * LP;
;   uint4 pq, pk; bf16_t pv; float pg = 0.f, pb = 0.f;
;     ...
;   __syncthreads();
;   GDN_LOAD(PADR)
;   GDN_STORE(0)
;   __syncthreads();
.Lgd_item:
	s_setprio 3
	v_readlane_b32 s14, v244, 27
	v_readlane_b32 s8, v247, 3
	v_readlane_b32 s9, v247, 4
	v_readlane_b32 s4, v247, 1
	v_readlane_b32 s5, v247, 2
	v_and_b32_e32 v136, 15, v2
	v_lshrrev_b32_e32 v137, 4, v2
	v_bfe_u32 v138, v2, 4, 2
	v_lshrrev_b32_e32 v139, 6, v2
	s_lshr_b32 s10, s14, 5
	s_bfe_u32 s11, s14, 0x20003
	s_and_b32 s12, s14, 7
	s_lshl_b32 s12, s12, 5
	s_mul_i32 s13, s10, 0x2080
	s_add_i32 s13, s13, 0x70
	s_add_u32 s6, s8, 0x19c8c000
	s_addc_u32 s7, s9, 0
	s_add_u32 s8, s8, 0x19d90000
	s_addc_u32 s9, s9, 0
	s_lshl_b32 s14, s10, 2
	s_add_i32 s14, s14, s11
	s_mul_i32 s14, s14, 0x80400
	s_add_u32 s10, s4, 0x71a0000
	s_addc_u32 s15, s5, 0
	s_add_u32 s10, s10, s14
	s_addc_u32 s11, s15, 0
	v_readfirstlane_b32 s100, v139
	v_lshlrev_b32_e32 v151, 9, v136
	v_lshl_add_u32 v151, v139, 7, v151
	v_lshl_add_u32 v151, v138, 4, v151
	v_lshlrev_b32_e32 v152, 11, v138
	v_lshl_add_u32 v152, v139, 7, v152
	v_lshl_add_u32 v152, v136, 2, v152
	v_lshlrev_b32_e32 v153, 6, v136
	v_lshl_add_u32 v153, v138, 4, v153
	v_lshlrev_b32_e32 v154, 4, v138
	v_and_b32_e32 v140, 63, v2
	v_lshlrev_b32_e32 v156, 4, v140
	v_add_u32_e32 v156, 0x8a00, v156
	s_mul_i32 s101, s100, 0xc00
	v_add_u32_e32 v155, s101, v156
	v_lshlrev_b32_e32 v157, 5, v2
	v_lshl_add_u32 v158, v136, 4, v137
	v_lshlrev_b32_e32 v158, 2, v158
	v_add_u32_e32 v158, 16384, v158
	v_lshlrev_b32_e32 v159, 2, v136
	v_lshlrev_b32_e32 v141, 2, v138
	v_add_u32_e32 v142, 0, v141
	v_cmp_le_u32_e32 vcc, v142, v136
	s_nop 1
	v_cndmask_b32_e64 v166, 0, 1.0, vcc
	v_add_u32_e32 v142, 1, v141
	v_cmp_le_u32_e32 vcc, v142, v136
	s_nop 1
	v_cndmask_b32_e64 v167, 0, 1.0, vcc
	v_add_u32_e32 v142, 2, v141
	v_cmp_le_u32_e32 vcc, v142, v136
	s_nop 1
	v_cndmask_b32_e64 v168, 0, 1.0, vcc
	v_add_u32_e32 v142, 3, v141
	v_cmp_le_u32_e32 vcc, v142, v136
	s_nop 1
	v_cndmask_b32_e64 v169, 0, 1.0, vcc
	v_readlane_b32 s101, v244, 27
	s_bfe_u32 s101, s101, 0x20003
	v_add_u32_e32 v142, s13, v137
	s_lshl_b32 s14, s101, 8
	v_lshl_add_u32 v143, v136, 4, s14
	s_movk_i32 s15, 0xc00
	v_mad_u32_u24 v118, v142, s15, v143
	s_add_i32 s14, s14, s12
	v_lshl_add_u32 v143, v136, 1, s14
	v_mad_u32_u24 v119, v142, s15, v143
	v_add_u32_e32 v119, 0x800, v119
	v_add_u32_e32 v142, s13, v136
	s_lshl_b32 s15, s101, 2
	v_lshl_add_u32 v140, v142, 5, s15
	v_add_u32_e32 v142, s13, v141
	v_lshl_add_u32 v57, v142, 11, v143
	v_add_u32_e32 v57, 0x400, v57
	v_add_u32_e32 v58, 0x1000, v57
	v_lshlrev_b32_e32 v59, 6, v136
	v_lshl_add_u32 v59, v138, 4, v59
	v_mov_b32_e32 v12, 0
	v_mov_b32_e32 v13, 0
	v_mov_b32_e32 v14, 0
	v_mov_b32_e32 v15, 0
	v_mov_b32_e32 v16, 0
	v_mov_b32_e32 v17, 0
	v_mov_b32_e32 v18, 0
	v_mov_b32_e32 v19, 0
	s_barrier
	global_load_dwordx4 v[108:111], v118, s[4:5]
	global_load_dwordx4 v[112:115], v118, s[4:5] offset:1024
	global_load_ushort v116, v119, s[4:5]
	global_load_dword v117, v140, s[6:7]
	global_load_dwordx4 v[88:91], v59, s[10:11]
	v_mov_b32_e32 v148, v157
	v_mov_b32_e32 v149, v158
	v_mov_b32_e32 v150, v159
	s_waitcnt vmcnt(0)
	v_lshlrev_b32_e32 v120, 16, v108
	v_and_b32_e32 v121, 0xffff0000, v108
	v_lshlrev_b32_e32 v122, 16, v109
	v_and_b32_e32 v123, 0xffff0000, v109
	v_lshlrev_b32_e32 v124, 16, v110
	v_and_b32_e32 v125, 0xffff0000, v110
	v_lshlrev_b32_e32 v126, 16, v111
	v_and_b32_e32 v127, 0xffff0000, v111
	v_lshlrev_b32_e32 v128, 16, v112
	v_and_b32_e32 v129, 0xffff0000, v112
	v_lshlrev_b32_e32 v130, 16, v113
	v_and_b32_e32 v131, 0xffff0000, v113
	v_lshlrev_b32_e32 v132, 16, v114
	v_and_b32_e32 v133, 0xffff0000, v114
	v_lshlrev_b32_e32 v134, 16, v115
	v_and_b32_e32 v135, 0xffff0000, v115
	v_mov_b32_e32 v136, v117
	v_lshlrev_b32_e32 v137, 16, v116
	ds_write_b128 v148, v[120:123]
	v_add_f32_dpp v136, v136, v136 row_shr:1 row_mask:0xf bank_mask:0xf bound_ctrl:1
	ds_write_b128 v148, v[124:127] offset:16
	ds_write_b128 v148, v[128:131] offset:8192
	v_add_f32_dpp v136, v136, v136 row_shr:2 row_mask:0xf bank_mask:0xf bound_ctrl:1
	ds_write_b128 v148, v[132:135] offset:8208
	ds_write_b32 v149, v137
	v_add_f32_dpp v136, v136, v136 row_shr:4 row_mask:0xf bank_mask:0xf bound_ctrl:1
	s_nop 1
	v_add_f32_dpp v136, v136, v136 row_shr:8 row_mask:0xf bank_mask:0xf bound_ctrl:1
	s_nop 0
	v_max_f32_e32 v136, 0xc2a00000, v136
	v_mul_f32_e32 v136, 0x3fb8aa3b, v136
	v_exp_f32_e32 v138, v136
	v_exp_f32_e64 v139, -v136
	s_nop 0
	v_mul_f32_e32 v136, 0x3db504f3, v138
	ds_write_b32 v150, v139 offset:17408
	ds_write_b32 v150, v138 offset:17536
	ds_write_b32 v150, v136 offset:17472
	s_add_u32 s4, s4, 0xc000
	s_addc_u32 s5, s5, 0
	s_add_u32 s6, s6, 0x200
	s_addc_u32 s7, s7, 0
	s_add_u32 s10, s10, 0x400
	s_addc_u32 s11, s11, 0
	s_mov_b32 s0, 0
	s_mov_b32 s1, 0
	s_waitcnt lgkmcnt(0)
	s_barrier
.Lgd_chunk:
	v_add_u32_e32 v141, s1, v151
	v_add_u32_e32 v142, s1, v152
	v_add_u32_e32 v143, s1, v153
	v_add_u32_e32 v144, s1, v154
	v_mov_b32_e32 v145, s1
	s_xor_b32 s2, s1, 0x4500
	s_and_b32 s12, s0, 1
	s_mul_i32 s12, s12, 0x3000
	v_add_u32_e32 v146, s12, v155
	v_add_u32_e32 v147, s12, v156
	ds_read_b128 v[20:23], v141 offset:8192
	ds_read_b128 v[28:31], v141 offset:0
	ds_read_b128 v[24:27], v141 offset:8256
	ds_read_b128 v[32:35], v141 offset:64
	s_cmp_eq_u32 s0, 512
	s_cbranch_scc1 .Lgd_noload
	global_load_dwordx4 v[108:111], v118, s[4:5]
	global_load_dwordx4 v[112:115], v118, s[4:5] offset:1024
	global_load_ushort v116, v119, s[4:5]
	global_load_dword v117, v140, s[6:7]
	global_load_dwordx4 v[92:95], v59, s[10:11]
; __device__ __forceinline__ void gdn_item(const Params& p, int item, float* sm) {
;     ...
;       for (int t = 0; t < TC; t++) {
;         const float4 k0 = *(const float4*)(bk + t * 128 + sub * 4);
;         const float4 k1 = *(const float4*)(bk + t * 128 + 64 + sub * 4);
;         const float4 q0 = *(const float4*)(bq + t * 128 + sub * 4);
;         const float4 q1 = *(const float4*)(bq + t * 128 + 64 + sub * 4);
;         const float v = bv[t * 16 + cw];
;         const float g = bg[t], be = bg[TC + t];
;         const float qk = bo[TC * 16 + t];
;         float pa = k0.x * S[0] + k0.y * S[1];
;         float pb2 = k0.z * S[2] + k0.w * S[3];
;         float qa = q0.x * S[0] + q0.y * S[1];
;         float qb2 = q0.z * S[2] + q0.w * S[3];
;         pa += k1.x * S[4] + k1.y * S[5];
;         pb2 += k1.z * S[6] + k1.w * S[7];
;         qa += q1.x * S[4] + q1.y * S[5];
;         qb2 += q1.z * S[6] + q1.w * S[7];
;         const float ks = dpp_sum16(pa + pb2);
;         const float qs = dpp_sum16(qa + qb2);
;         const float coef = be * (v - g * ks);
;         const float oo = g * qs + coef * qk;
;         S[0] = g * S[0] + coef * k0.x; S[1] = g * S[1] + coef * k0.y; S[2] = g * S[2] + coef * k0.z; S[3] = g * S[3] + coef * k0.w;
;         S[4] = g * S[4] + coef * k1.x; S[5] = g * S[5] + coef * k1.y; S[6] = g * S[6] + coef * k1.z; S[7] = g * S[7] + coef * k1.w;
;         oreg[t] = oo * 0.08838834764831845f;
.Lgd_noload:
	v_add_u32_e32 v148, s2, v157
	v_add_u32_e32 v149, s2, v158
	v_add_u32_e32 v150, s2, v159
	s_waitcnt lgkmcnt(0)
	v_mfma_f32_16x16x4_f32 v[60:63], v20, v12, 0
	ds_read_b32 v36, v142 offset:8192
	v_mfma_f32_16x16x4_f32 v[64:67], v28, v12, 0
	ds_read_b32 v37, v142 offset:8704
	v_mfma_f32_16x16x4_f32 v[68:71], v20, v28, 0
	v_mfma_f32_16x16x4_f32 v[60:63], v21, v13, v[60:63]
	ds_read_b32 v38, v142 offset:9216
	v_mfma_f32_16x16x4_f32 v[64:67], v29, v13, v[64:67]
	ds_read_b32 v39, v142 offset:9728
	v_mfma_f32_16x16x4_f32 v[68:71], v21, v29, v[68:71]
	v_mfma_f32_16x16x4_f32 v[60:63], v22, v14, v[60:63]
	ds_read_b32 v40, v142 offset:8256
	v_mfma_f32_16x16x4_f32 v[64:67], v30, v14, v[64:67]
	ds_read_b32 v41, v142 offset:8768
	v_mfma_f32_16x16x4_f32 v[68:71], v22, v30, v[68:71]
	v_mfma_f32_16x16x4_f32 v[60:63], v23, v15, v[60:63]
	ds_read_b32 v42, v142 offset:9280
	v_mfma_f32_16x16x4_f32 v[64:67], v31, v15, v[64:67]
	ds_read_b32 v43, v142 offset:9792
	v_mfma_f32_16x16x4_f32 v[68:71], v23, v31, v[68:71]
	v_mfma_f32_16x16x4_f32 v[60:63], v24, v16, v[60:63]
	ds_read_b128 v[44:47], v143 offset:16384
	v_mfma_f32_16x16x4_f32 v[64:67], v32, v16, v[64:67]
	ds_read_b128 v[48:51], v144 offset:17408
	v_mfma_f32_16x16x4_f32 v[68:71], v24, v32, v[68:71]
	v_mfma_f32_16x16x4_f32 v[60:63], v25, v17, v[60:63]
	ds_read_b128 v[52:55], v144 offset:17472
	v_mfma_f32_16x16x4_f32 v[64:67], v33, v17, v[64:67]
	ds_read_b32 v56, v145 offset:17596
	v_mfma_f32_16x16x4_f32 v[68:71], v25, v33, v[68:71]
	v_mfma_f32_16x16x4_f32 v[60:63], v26, v18, v[60:63]
	v_mfma_f32_16x16x4_f32 v[64:67], v34, v18, v[64:67]
	v_mfma_f32_16x16x4_f32 v[68:71], v26, v34, v[68:71]
	v_mfma_f32_16x16x4_f32 v[60:63], v27, v19, v[60:63]
	v_mfma_f32_16x16x4_f32 v[64:67], v35, v19, v[64:67]
	v_mfma_f32_16x16x4_f32 v[68:71], v27, v35, v[68:71]
	s_cmp_eq_u32 s0, 512
	s_cbranch_scc1 .Lgd_noprep
	s_waitcnt vmcnt(0)
	v_lshlrev_b32_e32 v120, 16, v108
	v_and_b32_e32 v121, 0xffff0000, v108
	v_lshlrev_b32_e32 v122, 16, v109
	v_and_b32_e32 v123, 0xffff0000, v109
	v_lshlrev_b32_e32 v124, 16, v110
	v_and_b32_e32 v125, 0xffff0000, v110
	v_lshlrev_b32_e32 v126, 16, v111
	v_and_b32_e32 v127, 0xffff0000, v111
	v_lshlrev_b32_e32 v128, 16, v112
	v_and_b32_e32 v129, 0xffff0000, v112
	v_lshlrev_b32_e32 v130, 16, v113
	v_and_b32_e32 v131, 0xffff0000, v113
	v_lshlrev_b32_e32 v132, 16, v114
	v_and_b32_e32 v133, 0xffff0000, v114
	v_lshlrev_b32_e32 v134, 16, v115
	v_and_b32_e32 v135, 0xffff0000, v115
	v_mov_b32_e32 v136, v117
	v_lshlrev_b32_e32 v137, 16, v116
	ds_write_b128 v148, v[120:123]
	v_add_f32_dpp v136, v136, v136 row_shr:1 row_mask:0xf bank_mask:0xf bound_ctrl:1
	ds_write_b128 v148, v[124:127] offset:16
	ds_write_b128 v148, v[128:131] offset:8192
	v_add_f32_dpp v136, v136, v136 row_shr:2 row_mask:0xf bank_mask:0xf bound_ctrl:1
	ds_write_b128 v148, v[132:135] offset:8208
	ds_write_b32 v149, v137
	v_add_f32_dpp v136, v136, v136 row_shr:4 row_mask:0xf bank_mask:0xf bound_ctrl:1
	s_nop 1
	v_add_f32_dpp v136, v136, v136 row_shr:8 row_mask:0xf bank_mask:0xf bound_ctrl:1
	s_nop 0
	v_max_f32_e32 v136, 0xc2a00000, v136
	v_mul_f32_e32 v136, 0x3fb8aa3b, v136
	v_exp_f32_e32 v138, v136
	v_exp_f32_e64 v139, -v136
	s_nop 0
	v_mul_f32_e32 v136, 0x3db504f3, v138
	ds_write_b32 v150, v139 offset:17408
	ds_write_b32 v150, v138 offset:17536
	ds_write_b32 v150, v136 offset:17472
	s_add_u32 s4, s4, 0xc000
	s_addc_u32 s5, s5, 0
	s_add_u32 s6, s6, 0x200
	s_addc_u32 s7, s7, 0
	s_add_u32 s10, s10, 0x400
	s_addc_u32 s11, s11, 0
; __device__ __forceinline__ void gdn_item(const Params& p, int item, float* sm) {
;     ...
;         const float ks = dpp_sum16(pa + pb2);
;         const float qs = dpp_sum16(qa + qb2);
;         const float coef = be * (v - g * ks);
;         const float oo = g * qs + coef * qk;
;         S[0] = g * S[0] + coef * k0.x; S[1] = g * S[1] + coef * k0.y; S[2] = g * S[2] + coef * k0.z; S[3] = g * S[3] + coef * k0.w;
;         S[4] = g * S[4] + coef * k1.x; S[5] = g * S[5] + coef * k1.y; S[6] = g * S[6] + coef * k1.z; S[7] = g * S[7] + coef * k1.w;
;         oreg[t] = oo * 0.08838834764831845f;
;       }
;       if (sub == 0) {
; #pragma unroll
;         for (int t = 0; t < TC; t++) bo[t * 16 + cw] = oreg[t];
;       }
;     }
;     if (ch + 1 < NCH) GDN_STORE(bi ^ 1)
;     __syncthreads();
;     {
;       const float ov = sm[bi * BUF + 2 * TC * 128 + TC * 16 + 2 * TC + ltt * 16 + lseg];
;       O[(rowb + t0 + ltt) * D + 512 + h * 128 + c0 + lseg] = f2bf(ov);
.Lgd_noprep:
	s_nop 7
	s_nop 3
	ds_write_b128 v146, v[60:63]
	ds_write_b128 v146, v[64:67] offset:1024
	ds_write_b128 v146, v[68:71] offset:2048
	s_waitcnt lgkmcnt(0)
	s_barrier
	ds_read_b128 v[72:75], v147 offset:0
	ds_read_b128 v[76:79], v147 offset:3072
	ds_read_b128 v[80:83], v147 offset:6144
	ds_read_b128 v[84:87], v147 offset:9216
	s_waitcnt lgkmcnt(0)
	v_add_f32_e32 v72, v72, v76
	v_add_f32_e32 v80, v80, v84
	v_add_f32_e32 v73, v73, v77
	v_add_f32_e32 v81, v81, v85
	v_add_f32_e32 v74, v74, v78
	v_add_f32_e32 v82, v82, v86
	v_add_f32_e32 v75, v75, v79
	v_add_f32_e32 v83, v83, v87
	v_add_f32_e32 v72, v72, v80
	v_add_f32_e32 v73, v73, v81
	v_add_f32_e32 v74, v74, v82
	v_add_f32_e32 v75, v75, v83
	v_fma_f32 v96, v44, v48, -v72
	v_fma_f32 v97, v45, v49, -v73
	v_fma_f32 v98, v46, v50, -v74
	v_fma_f32 v99, v47, v51, -v75
	s_nop 1
	v_mfma_f32_16x16x4_f32 v[100:103], v88, v96, 0
	v_mfma_f32_16x16x4_f32 v[100:103], v89, v97, v[100:103]
	v_mfma_f32_16x16x4_f32 v[100:103], v90, v98, v[100:103]
	v_mfma_f32_16x16x4_f32 v[100:103], v91, v99, v[100:103]
	s_and_b32 s12, s0, 3
	s_cmp_eq_u32 s12, s100
	s_cbranch_scc0 .Lgd_upd
	ds_read_b128 v[72:75], v147 offset:1024
	ds_read_b128 v[76:79], v147 offset:4096
	ds_read_b128 v[80:83], v147 offset:7168
	ds_read_b128 v[84:87], v147 offset:10240
	s_waitcnt lgkmcnt(0)
	v_add_f32_e32 v72, v72, v76
	v_add_f32_e32 v80, v80, v84
	v_add_f32_e32 v73, v73, v77
	v_add_f32_e32 v81, v81, v85
	v_add_f32_e32 v74, v74, v78
	v_add_f32_e32 v82, v82, v86
	v_add_f32_e32 v75, v75, v79
	v_add_f32_e32 v83, v83, v87
	v_add_f32_e32 v104, v72, v80
	v_add_f32_e32 v105, v73, v81
	v_add_f32_e32 v106, v74, v82
	v_add_f32_e32 v107, v75, v83
	ds_read_b128 v[72:75], v147 offset:2048
	ds_read_b128 v[76:79], v147 offset:5120
	ds_read_b128 v[80:83], v147 offset:8192
	ds_read_b128 v[84:87], v147 offset:11264
	s_waitcnt lgkmcnt(0)
	v_add_f32_e32 v72, v72, v76
	v_add_f32_e32 v80, v80, v84
	v_add_f32_e32 v73, v73, v77
	v_add_f32_e32 v81, v81, v85
	v_add_f32_e32 v74, v74, v78
	v_add_f32_e32 v82, v82, v86
	v_add_f32_e32 v75, v75, v79
	v_add_f32_e32 v83, v83, v87
	v_add_f32_e32 v72, v72, v80
	v_add_f32_e32 v73, v73, v81
	v_add_f32_e32 v74, v74, v82
	v_add_f32_e32 v75, v75, v83
	v_mul_f32_e32 v72, v72, v166
	v_mul_f32_e32 v73, v73, v167
	v_mul_f32_e32 v74, v74, v168
	v_mul_f32_e32 v75, v75, v169
	s_nop 7
	s_nop 1
	v_mfma_f32_16x16x4_f32 v[104:107], v72, v100, v[104:107]
	v_mfma_f32_16x16x4_f32 v[104:107], v73, v101, v[104:107]
	v_mfma_f32_16x16x4_f32 v[104:107], v74, v102, v[104:107]
	v_mfma_f32_16x16x4_f32 v[104:107], v75, v103, v[104:107]
.Lgd_upd:
	s_nop 7
	s_nop 3
	v_mfma_f32_16x16x4_f32 v[12:15], v36, v100, v[12:15]
	v_mfma_f32_16x16x4_f32 v[16:19], v40, v100, v[16:19]
	v_mfma_f32_16x16x4_f32 v[12:15], v37, v101, v[12:15]
	v_mfma_f32_16x16x4_f32 v[16:19], v41, v101, v[16:19]
	v_mfma_f32_16x16x4_f32 v[12:15], v38, v102, v[12:15]
	v_mfma_f32_16x16x4_f32 v[16:19], v42, v102, v[16:19]
	v_mfma_f32_16x16x4_f32 v[12:15], v39, v103, v[12:15]
	v_mfma_f32_16x16x4_f32 v[16:19], v43, v103, v[16:19]
	s_cmp_eq_u32 s12, s100
	s_cbranch_scc0 .Lgd_noout
	s_nop 7
	s_nop 3
	v_mul_f32_e32 v104, v104, v52
	v_mul_f32_e32 v105, v105, v53
	v_mul_f32_e32 v106, v106, v54
	v_mul_f32_e32 v107, v107, v55
	v_cvt_pk_bf16_f32 v104, v104, v104
	v_cvt_pk_bf16_f32 v105, v105, v105
	v_cvt_pk_bf16_f32 v106, v106, v106
	v_cvt_pk_bf16_f32 v107, v107, v107
	global_store_short v57, v104, s[8:9]
	global_store_short v57, v105, s[8:9] offset:2048
	global_store_short v58, v106, s[8:9]
	global_store_short v58, v107, s[8:9] offset:2048
.Lgd_noout:
	s_add_u32 s8, s8, 0x8000
	s_addc_u32 s9, s9, 0
	v_mov_b32_e32 v88, v92
	v_mov_b32_e32 v89, v93
	v_mov_b32_e32 v90, v94
	v_mov_b32_e32 v91, v95
	s_nop 7
	s_nop 3
	v_mul_f32_e32 v12, v12, v56
	v_mul_f32_e32 v13, v13, v56
	v_mul_f32_e32 v14, v14, v56
	v_mul_f32_e32 v15, v15, v56
	v_mul_f32_e32 v16, v16, v56
	v_mul_f32_e32 v17, v17, v56
	v_mul_f32_e32 v18, v18, v56
	v_mul_f32_e32 v19, v19, v56
	s_mov_b32 s1, s2
	s_add_i32 s0, s0, 1
	s_cmp_lg_u32 s0, 513
	s_cbranch_scc1 .Lgd_chunk
	s_waitcnt lgkmcnt(0)
	s_setprio 0

; __device__ __forceinline__ unsigned xb_xcc_id() { return (unsigned)__builtin_amdgcn_s_getreg((3 << 11) | 20) & 0xFu; }
; __global__ void __launch_bounds__(256, 2) mega_kernel(Params p) {
;     ...
;   const unsigned xcc = xb_xcc_id();
;   unsigned nloc = 0u, nx = 0u;
.LBB0_2890:
	v_mov_b32_e32 v243, 0

; __global__ void __launch_bounds__(256, 2) mega_kernel(Params p) {
;     ...
;     if (ph + 1 < NPHASE) {
;       if (ph == 0) grid.sync();
;       else xcd_barrier(bar, xcc, nloc, nx);
.LBB0_2962:
	s_waitcnt lgkmcnt(0)
	v_readfirstlane_b32 s0, v243
	s_cmp_eq_u32 s24, 5
	s_cbranch_scc0 .Lmv_skip
	s_cmp_eq_u32 s0, 1
	s_cbranch_scc1 .Lmv_skip
	v_readlane_b32 s2, v244, 27
	v_readlane_b32 s4, v247, 1
	v_readlane_b32 s5, v247, 2
	v_readlane_b32 s6, v247, 3
	v_readlane_b32 s7, v247, 4
	v_lshrrev_b32_e32 v156, 6, v2
	v_and_b32_e32 v157, 63, v2
	s_add_u32 s6, s6, 0x19c8c000
	s_addc_u32 s7, s7, 0
	s_add_u32 s8, s4, 0x71a0000
	s_addc_u32 s9, s5, 0
	v_readfirstlane_b32 s10, v156
	v_and_b32_e32 v152, 15, v157
	v_lshrrev_b32_e32 v158, 4, v157
	s_lshl_b32 s2, s2, 2
	s_add_i32 s2, s2, s10
	v_readlane_b32 s11, v247, 0
	s_lshl_b32 s11, s11, 2
	s_lshl_b32 s12, s10, 11
	v_mul_u32_u24_e32 v153, 0xc00, v152
	v_lshl_add_u32 v153, v158, 6, v153
	v_lshlrev_b32_e32 v154, 5, v152
	v_lshlrev_b32_e32 v155, 6, v152
	v_lshl_add_u32 v155, v158, 4, v155
	v_add_u32_e32 v155, s12, v155
.Lmv_item:
	s_cmp_ge_u32 s2, 0x2010
	s_cbranch_scc1 .Lmv_done
	s_mul_hi_u32 s13, s2, 0x7fc020
	s_mul_i32 s14, s13, 0x201
	s_sub_u32 s14, s2, s14
	s_lshr_b32 s15, s13, 2
	s_and_b32 s16, s13, 3
	s_mul_i32 s17, s15, 0x2080
	s_lshl_b32 s18, s14, 4
	s_add_i32 s17, s17, s18
	s_add_i32 s17, s17, 0x70
	s_mul_i32 s18, s17, 0xc00
	s_lshl_b32 s19, s16, 8
	s_add_i32 s18, s18, s19
	s_add_i32 s18, s18, 0x400
	v_add_u32_e32 v156, s18, v153
	s_lshl_b32 s19, s17, 5
	s_lshl_b32 s20, s16, 2
	s_add_i32 s19, s19, s20
	s_add_i32 s19, s19, 16
	v_add_u32_e32 v157, s19, v154
	global_load_dwordx4 v[64:67], v156, s[4:5]
	global_load_dwordx4 v[68:71], v156, s[4:5] offset:16
	global_load_dwordx4 v[72:75], v156, s[4:5] offset:32
	global_load_dwordx4 v[76:79], v156, s[4:5] offset:48
	global_load_dword v158, v157, s[6:7]
	s_waitcnt vmcnt(0)
	v_lshlrev_b32_e32 v32, 16, v64
	v_and_b32_e32 v33, 0xffff0000, v64
	v_lshlrev_b32_e32 v34, 16, v65
	v_and_b32_e32 v35, 0xffff0000, v65
	v_lshlrev_b32_e32 v36, 16, v66
	v_and_b32_e32 v37, 0xffff0000, v66
	v_lshlrev_b32_e32 v38, 16, v67
	v_and_b32_e32 v39, 0xffff0000, v67
	v_lshlrev_b32_e32 v40, 16, v68
	v_and_b32_e32 v41, 0xffff0000, v68
	v_lshlrev_b32_e32 v42, 16, v69
	v_and_b32_e32 v43, 0xffff0000, v69
	v_lshlrev_b32_e32 v44, 16, v70
	v_and_b32_e32 v45, 0xffff0000, v70
	v_lshlrev_b32_e32 v46, 16, v71
	v_and_b32_e32 v47, 0xffff0000, v71
	v_lshlrev_b32_e32 v48, 16, v72
	v_and_b32_e32 v49, 0xffff0000, v72
	v_lshlrev_b32_e32 v50, 16, v73
	v_and_b32_e32 v51, 0xffff0000, v73
	v_lshlrev_b32_e32 v52, 16, v74
	v_and_b32_e32 v53, 0xffff0000, v74
	v_lshlrev_b32_e32 v54, 16, v75
	v_and_b32_e32 v55, 0xffff0000, v75
	v_lshlrev_b32_e32 v56, 16, v76
	v_and_b32_e32 v57, 0xffff0000, v76
	v_lshlrev_b32_e32 v58, 16, v77
	v_and_b32_e32 v59, 0xffff0000, v77
	v_lshlrev_b32_e32 v60, 16, v78
	v_and_b32_e32 v61, 0xffff0000, v78
	v_lshlrev_b32_e32 v62, 16, v79
	v_and_b32_e32 v63, 0xffff0000, v79
	v_lshl_add_u32 v156, v152, 2, s12
	ds_write_b32 v156, v158 offset:1024
	v_mfma_f32_16x16x4_f32 v[80:83], v32, v32, 0
	v_mfma_f32_16x16x4_f32 v[84:87], v33, v33, 0
	v_mfma_f32_16x16x4_f32 v[80:83], v34, v34, v[80:83]
	v_mfma_f32_16x16x4_f32 v[84:87], v35, v35, v[84:87]
	v_mfma_f32_16x16x4_f32 v[80:83], v36, v36, v[80:83]
	v_mfma_f32_16x16x4_f32 v[84:87], v37, v37, v[84:87]
	v_mfma_f32_16x16x4_f32 v[80:83], v38, v38, v[80:83]
	v_mfma_f32_16x16x4_f32 v[84:87], v39, v39, v[84:87]
	v_mfma_f32_16x16x4_f32 v[80:83], v40, v40, v[80:83]
	v_mfma_f32_16x16x4_f32 v[84:87], v41, v41, v[84:87]
	v_mfma_f32_16x16x4_f32 v[80:83], v42, v42, v[80:83]
	v_mfma_f32_16x16x4_f32 v[84:87], v43, v43, v[84:87]
	v_mfma_f32_16x16x4_f32 v[80:83], v44, v44, v[80:83]
	v_mfma_f32_16x16x4_f32 v[84:87], v45, v45, v[84:87]
	v_mfma_f32_16x16x4_f32 v[80:83], v46, v46, v[80:83]
	v_mfma_f32_16x16x4_f32 v[84:87], v47, v47, v[84:87]
	v_mfma_f32_16x16x4_f32 v[80:83], v48, v48, v[80:83]
	v_mfma_f32_16x16x4_f32 v[84:87], v49, v49, v[84:87]
	v_mfma_f32_16x16x4_f32 v[80:83], v50, v50, v[80:83]
	v_mfma_f32_16x16x4_f32 v[84:87], v51, v51, v[84:87]
	v_mfma_f32_16x16x4_f32 v[80:83], v52, v52, v[80:83]
	v_mfma_f32_16x16x4_f32 v[84:87], v53, v53, v[84:87]
	v_mfma_f32_16x16x4_f32 v[80:83], v54, v54, v[80:83]
	v_mfma_f32_16x16x4_f32 v[84:87], v55, v55, v[84:87]
	v_mfma_f32_16x16x4_f32 v[80:83], v56, v56, v[80:83]
	v_mfma_f32_16x16x4_f32 v[84:87], v57, v57, v[84:87]
	v_mfma_f32_16x16x4_f32 v[80:83], v58, v58, v[80:83]
	v_mfma_f32_16x16x4_f32 v[84:87], v59, v59, v[84:87]
	v_mfma_f32_16x16x4_f32 v[80:83], v60, v60, v[80:83]
	v_mfma_f32_16x16x4_f32 v[84:87], v61, v61, v[84:87]
	v_mfma_f32_16x16x4_f32 v[80:83], v62, v62, v[80:83]
	v_mfma_f32_16x16x4_f32 v[84:87], v63, v63, v[84:87]
	v_mov_b32_e32 v157, s12
	s_waitcnt lgkmcnt(0)
	ds_read_b128 v[88:91], v157 offset:1024
	ds_read_b128 v[92:95], v157 offset:1040
	ds_read_b128 v[96:99], v157 offset:1056
	ds_read_b128 v[100:103], v157 offset:1072
	s_nop 7
	s_nop 3
	v_add_f32_e32 v80, v80, v84
	v_add_f32_e32 v81, v81, v85
	v_add_f32_e32 v82, v82, v86
	v_add_f32_e32 v83, v83, v87
	ds_write_b128 v155, v[80:83]
	s_waitcnt lgkmcnt(0)
	ds_read_b128 v[136:139], v157 offset:64
	v_cmp_eq_u32_e32 vcc, 0, v152
	s_nop 1
	v_cndmask_b32_e64 v159, 0, 1.0, vcc
	v_mul_f32_e32 v104, v88, v159
	ds_read_b128 v[120:123], v157 offset:128
	v_cmp_eq_u32_e32 vcc, 1, v152
	s_waitcnt lgkmcnt(1)
	s_nop 0
	v_cndmask_b32_e64 v159, 0, 1.0, vcc
	v_fma_f32 v159, -v136, v104, v159
	v_mul_f32_e32 v105, v89, v159
	ds_read_b128 v[136:139], v157 offset:192
	v_cmp_eq_u32_e32 vcc, 2, v152
	s_waitcnt lgkmcnt(1)
	s_nop 0
	v_cndmask_b32_e64 v159, 0, 1.0, vcc
	v_fma_f32 v159, -v120, v104, v159
	v_fma_f32 v159, -v121, v105, v159
	v_mul_f32_e32 v106, v90, v159
	ds_read_b128 v[120:123], v157 offset:256
	v_cmp_eq_u32_e32 vcc, 3, v152
	s_waitcnt lgkmcnt(1)
; __device__ __forceinline__ void gdn_item(const Params& p, int item, float* sm) {
;     ...
;       for (int t = 0; t < TC; t++) {
;         const float4 k0 = *(const float4*)(bk + t * 128 + sub * 4);
;         const float4 k1 = *(const float4*)(bk + t * 128 + 64 + sub * 4);
;         const float4 q0 = *(const float4*)(bq + t * 128 + sub * 4);
;         const float4 q1 = *(const float4*)(bq + t * 128 + 64 + sub * 4);
;         const float v = bv[t * 16 + cw];
;         const float g = bg[t], be = bg[TC + t];
;         const float qk = bo[TC * 16 + t];
;         float pa = k0.x * S[0] + k0.y * S[1];
;         float pb2 = k0.z * S[2] + k0.w * S[3];
;         float qa = q0.x * S[0] + q0.y * S[1];
;         float qb2 = q0.z * S[2] + q0.w * S[3];
;         pa += k1.x * S[4] + k1.y * S[5];
;         pb2 += k1.z * S[6] + k1.w * S[7];
;         qa += q1.x * S[4] + q1.y * S[5];
;         qb2 += q1.z * S[6] + q1.w * S[7];
;         const float ks = dpp_sum16(pa + pb2);
;         const float qs = dpp_sum16(qa + qb2);
;         const float coef = be * (v - g * ks);
;         const float oo = g * qs + coef * qk;
;         S[0] = g * S[0] + coef * k0.x; S[1] = g * S[1] + coef * k0.y; S[2] = g * S[2] + coef * k0.z; S[3] = g * S[3] + coef * k0.w;
;         S[4] = g * S[4] + coef * k1.x; S[5] = g * S[5] + coef * k1.y; S[6] = g * S[6] + coef * k1.z; S[7] = g * S[7] + coef * k1.w;
;         oreg[t] = oo * 0.08838834764831845f;
	s_nop 0
	v_cndmask_b32_e64 v159, 0, 1.0, vcc
	v_fma_f32 v159, -v136, v104, v159
	v_fma_f32 v159, -v137, v105, v159
	v_fma_f32 v159, -v138, v106, v159
	v_mul_f32_e32 v107, v91, v159
	ds_read_b128 v[136:139], v157 offset:320
	ds_read_b128 v[140:143], v157 offset:336
	v_cmp_eq_u32_e32 vcc, 4, v152
	s_waitcnt lgkmcnt(2)
	s_nop 0
	v_cndmask_b32_e64 v159, 0, 1.0, vcc
	v_fma_f32 v159, -v120, v104, v159
	v_fma_f32 v159, -v121, v105, v159
	v_fma_f32 v159, -v122, v106, v159
	v_fma_f32 v159, -v123, v107, v159
	v_mul_f32_e32 v108, v92, v159
	ds_read_b128 v[120:123], v157 offset:384
	ds_read_b128 v[124:127], v157 offset:400
	v_cmp_eq_u32_e32 vcc, 5, v152
	s_waitcnt lgkmcnt(2)
	s_nop 0
	v_cndmask_b32_e64 v159, 0, 1.0, vcc
	v_fma_f32 v159, -v136, v104, v159
	v_fma_f32 v159, -v137, v105, v159
	v_fma_f32 v159, -v138, v106, v159
	v_fma_f32 v159, -v139, v107, v159
	v_fma_f32 v159, -v140, v108, v159
	v_mul_f32_e32 v109, v93, v159
	ds_read_b128 v[136:139], v157 offset:448
	ds_read_b128 v[140:143], v157 offset:464
	v_cmp_eq_u32_e32 vcc, 6, v152
	s_waitcnt lgkmcnt(2)
	s_nop 0
	v_cndmask_b32_e64 v159, 0, 1.0, vcc
	v_fma_f32 v159, -v120, v104, v159
	v_fma_f32 v159, -v121, v105, v159
	v_fma_f32 v159, -v122, v106, v159
	v_fma_f32 v159, -v123, v107, v159
	v_fma_f32 v159, -v124, v108, v159
	v_fma_f32 v159, -v125, v109, v159
	v_mul_f32_e32 v110, v94, v159
	ds_read_b128 v[120:123], v157 offset:512
	ds_read_b128 v[124:127], v157 offset:528
	v_cmp_eq_u32_e32 vcc, 7, v152
	s_waitcnt lgkmcnt(2)
	s_nop 0
	v_cndmask_b32_e64 v159, 0, 1.0, vcc
	v_fma_f32 v159, -v136, v104, v159
	v_fma_f32 v159, -v137, v105, v159
	v_fma_f32 v159, -v138, v106, v159
	v_fma_f32 v159, -v139, v107, v159
	v_fma_f32 v159, -v140, v108, v159
	v_fma_f32 v159, -v141, v109, v159
	v_fma_f32 v159, -v142, v110, v159
	v_mul_f32_e32 v111, v95, v159
	ds_read_b128 v[136:139], v157 offset:576
	ds_read_b128 v[140:143], v157 offset:592
	ds_read_b128 v[144:147], v157 offset:608
	v_cmp_eq_u32_e32 vcc, 8, v152
	s_waitcnt lgkmcnt(3)
	s_nop 0
	v_cndmask_b32_e64 v159, 0, 1.0, vcc
	v_fma_f32 v159, -v120, v104, v159
	v_fma_f32 v159, -v121, v105, v159
	v_fma_f32 v159, -v122, v106, v159
	v_fma_f32 v159, -v123, v107, v159
	v_fma_f32 v159, -v124, v108, v159
	v_fma_f32 v159, -v125, v109, v159
	v_fma_f32 v159, -v126, v110, v159
	v_fma_f32 v159, -v127, v111, v159
	v_mul_f32_e32 v112, v96, v159
	ds_read_b128 v[120:123], v157 offset:640
	ds_read_b128 v[124:127], v157 offset:656
	ds_read_b128 v[128:131], v157 offset:672
	v_cmp_eq_u32_e32 vcc, 9, v152
	s_waitcnt lgkmcnt(3)
	s_nop 0
	v_cndmask_b32_e64 v159, 0, 1.0, vcc
	v_fma_f32 v159, -v136, v104, v159
	v_fma_f32 v159, -v137, v105, v159
	v_fma_f32 v159, -v138, v106, v159
	v_fma_f32 v159, -v139, v107, v159
	v_fma_f32 v159, -v140, v108, v159
	v_fma_f32 v159, -v141, v109, v159
	v_fma_f32 v159, -v142, v110, v159
	v_fma_f32 v159, -v143, v111, v159
	v_fma_f32 v159, -v144, v112, v159
	v_mul_f32_e32 v113, v97, v159
	ds_read_b128 v[136:139], v157 offset:704
	ds_read_b128 v[140:143], v157 offset:720
	ds_read_b128 v[144:147], v157 offset:736
	v_cmp_eq_u32_e32 vcc, 10, v152
	s_waitcnt lgkmcnt(3)
	s_nop 0
	v_cndmask_b32_e64 v159, 0, 1.0, vcc
	v_fma_f32 v159, -v120, v104, v159
	v_fma_f32 v159, -v121, v105, v159
	v_fma_f32 v159, -v122, v106, v159
	v_fma_f32 v159, -v123, v107, v159
	v_fma_f32 v159, -v124, v108, v159
	v_fma_f32 v159, -v125, v109, v159
	v_fma_f32 v159, -v126, v110, v159
	v_fma_f32 v159, -v127, v111, v159
	v_fma_f32 v159, -v128, v112, v159
	v_fma_f32 v159, -v129, v113, v159
	v_mul_f32_e32 v114, v98, v159
	ds_read_b128 v[120:123], v157 offset:768
	ds_read_b128 v[124:127], v157 offset:784
	ds_read_b128 v[128:131], v157 offset:800
	v_cmp_eq_u32_e32 vcc, 11, v152
	s_waitcnt lgkmcnt(3)
; __device__ __forceinline__ void gdn_item(const Params& p, int item, float* sm) {
;     ...
;       for (int t = 0; t < TC; t++) {
;         const float4 k0 = *(const float4*)(bk + t * 128 + sub * 4);
;         const float4 k1 = *(const float4*)(bk + t * 128 + 64 + sub * 4);
;         const float4 q0 = *(const float4*)(bq + t * 128 + sub * 4);
;         const float4 q1 = *(const float4*)(bq + t * 128 + 64 + sub * 4);
;         const float v = bv[t * 16 + cw];
;         const float g = bg[t], be = bg[TC + t];
;         const float qk = bo[TC * 16 + t];
;         float pa = k0.x * S[0] + k0.y * S[1];
;         float pb2 = k0.z * S[2] + k0.w * S[3];
;         float qa = q0.x * S[0] + q0.y * S[1];
;         float qb2 = q0.z * S[2] + q0.w * S[3];
;         pa += k1.x * S[4] + k1.y * S[5];
;         pb2 += k1.z * S[6] + k1.w * S[7];
;         qa += q1.x * S[4] + q1.y * S[5];
;         qb2 += q1.z * S[6] + q1.w * S[7];
;         const float ks = dpp_sum16(pa + pb2);
;         const float qs = dpp_sum16(qa + qb2);
;         const float coef = be * (v - g * ks);
;         const float oo = g * qs + coef * qk;
;         S[0] = g * S[0] + coef * k0.x; S[1] = g * S[1] + coef * k0.y; S[2] = g * S[2] + coef * k0.z; S[3] = g * S[3] + coef * k0.w;
;         S[4] = g * S[4] + coef * k1.x; S[5] = g * S[5] + coef * k1.y; S[6] = g * S[6] + coef * k1.z; S[7] = g * S[7] + coef * k1.w;
;         oreg[t] = oo * 0.08838834764831845f;
	s_nop 0
	v_cndmask_b32_e64 v159, 0, 1.0, vcc
	v_fma_f32 v159, -v136, v104, v159
	v_fma_f32 v159, -v137, v105, v159
	v_fma_f32 v159, -v138, v106, v159
	v_fma_f32 v159, -v139, v107, v159
	v_fma_f32 v159, -v140, v108, v159
	v_fma_f32 v159, -v141, v109, v159
	v_fma_f32 v159, -v142, v110, v159
	v_fma_f32 v159, -v143, v111, v159
	v_fma_f32 v159, -v144, v112, v159
	v_fma_f32 v159, -v145, v113, v159
	v_fma_f32 v159, -v146, v114, v159
	v_mul_f32_e32 v115, v99, v159
	ds_read_b128 v[136:139], v157 offset:832
	ds_read_b128 v[140:143], v157 offset:848
	ds_read_b128 v[144:147], v157 offset:864
	ds_read_b128 v[148:151], v157 offset:880
	v_cmp_eq_u32_e32 vcc, 12, v152
	s_waitcnt lgkmcnt(4)
	s_nop 0
	v_cndmask_b32_e64 v159, 0, 1.0, vcc
	v_fma_f32 v159, -v120, v104, v159
	v_fma_f32 v159, -v121, v105, v159
	v_fma_f32 v159, -v122, v106, v159
	v_fma_f32 v159, -v123, v107, v159
	v_fma_f32 v159, -v124, v108, v159
	v_fma_f32 v159, -v125, v109, v159
	v_fma_f32 v159, -v126, v110, v159
	v_fma_f32 v159, -v127, v111, v159
	v_fma_f32 v159, -v128, v112, v159
	v_fma_f32 v159, -v129, v113, v159
	v_fma_f32 v159, -v130, v114, v159
	v_fma_f32 v159, -v131, v115, v159
	v_mul_f32_e32 v116, v100, v159
	ds_read_b128 v[120:123], v157 offset:896
	ds_read_b128 v[124:127], v157 offset:912
	ds_read_b128 v[128:131], v157 offset:928
	ds_read_b128 v[132:135], v157 offset:944
	v_cmp_eq_u32_e32 vcc, 13, v152
	s_waitcnt lgkmcnt(4)
	s_nop 0
	v_cndmask_b32_e64 v159, 0, 1.0, vcc
	v_fma_f32 v159, -v136, v104, v159
	v_fma_f32 v159, -v137, v105, v159
	v_fma_f32 v159, -v138, v106, v159
	v_fma_f32 v159, -v139, v107, v159
	v_fma_f32 v159, -v140, v108, v159
	v_fma_f32 v159, -v141, v109, v159
	v_fma_f32 v159, -v142, v110, v159
	v_fma_f32 v159, -v143, v111, v159
	v_fma_f32 v159, -v144, v112, v159
	v_fma_f32 v159, -v145, v113, v159
	v_fma_f32 v159, -v146, v114, v159
	v_fma_f32 v159, -v147, v115, v159
	v_fma_f32 v159, -v148, v116, v159
	v_mul_f32_e32 v117, v101, v159
	ds_read_b128 v[136:139], v157 offset:960
	ds_read_b128 v[140:143], v157 offset:976
	ds_read_b128 v[144:147], v157 offset:992
	ds_read_b128 v[148:151], v157 offset:1008
	v_cmp_eq_u32_e32 vcc, 14, v152
	s_waitcnt lgkmcnt(4)
	s_nop 0
	v_cndmask_b32_e64 v159, 0, 1.0, vcc
	v_fma_f32 v159, -v120, v104, v159
	v_fma_f32 v159, -v121, v105, v159
	v_fma_f32 v159, -v122, v106, v159
	v_fma_f32 v159, -v123, v107, v159
	v_fma_f32 v159, -v124, v108, v159
	v_fma_f32 v159, -v125, v109, v159
	v_fma_f32 v159, -v126, v110, v159
	v_fma_f32 v159, -v127, v111, v159
	v_fma_f32 v159, -v128, v112, v159
	v_fma_f32 v159, -v129, v113, v159
	v_fma_f32 v159, -v130, v114, v159
	v_fma_f32 v159, -v131, v115, v159
	v_fma_f32 v159, -v132, v116, v159
	v_fma_f32 v159, -v133, v117, v159
	v_mul_f32_e32 v118, v102, v159
	v_cmp_eq_u32_e32 vcc, 15, v152
	s_waitcnt lgkmcnt(0)
	s_nop 0
	v_cndmask_b32_e64 v159, 0, 1.0, vcc
	v_fma_f32 v159, -v136, v104, v159
	v_fma_f32 v159, -v137, v105, v159
	v_fma_f32 v159, -v138, v106, v159
	v_fma_f32 v159, -v139, v107, v159
	v_fma_f32 v159, -v140, v108, v159
	v_fma_f32 v159, -v141, v109, v159
	v_fma_f32 v159, -v142, v110, v159
	v_fma_f32 v159, -v143, v111, v159
	v_fma_f32 v159, -v144, v112, v159
	v_fma_f32 v159, -v145, v113, v159
	v_fma_f32 v159, -v146, v114, v159
	v_fma_f32 v159, -v147, v115, v159
	v_fma_f32 v159, -v148, v116, v159
	v_fma_f32 v159, -v149, v117, v159
	v_fma_f32 v159, -v150, v118, v159
	v_mul_f32_e32 v119, v103, v159
	s_lshl_b32 s13, s2, 10
	v_lshl_add_u32 v156, v152, 2, s13
	global_store_dword v156, v104, s[8:9]
	global_store_dword v156, v105, s[8:9] offset:64
	global_store_dword v156, v106, s[8:9] offset:128
	global_store_dword v156, v107, s[8:9] offset:192
	global_store_dword v156, v108, s[8:9] offset:256
	global_store_dword v156, v109, s[8:9] offset:320
	global_store_dword v156, v110, s[8:9] offset:384
	global_store_dword v156, v111, s[8:9] offset:448
	global_store_dword v156, v112, s[8:9] offset:512
	global_store_dword v156, v113, s[8:9] offset:576
	global_store_dword v156, v114, s[8:9] offset:640
	global_store_dword v156, v115, s[8:9] offset:704
	global_store_dword v156, v116, s[8:9] offset:768
	global_store_dword v156, v117, s[8:9] offset:832
	global_store_dword v156, v118, s[8:9] offset:896
	global_store_dword v156, v119, s[8:9] offset:960
	s_add_i32 s2, s2, s11
	s_branch .Lmv_item
.Lmv_done:
	v_mov_b32_e32 v243, 1
	s_waitcnt vmcnt(0)
	s_branch .Lbar_reenter
.Lmv_skip:
	s_getpc_b64 s[98:99]
